# static priority raise (s_setprio 1) for the second-dispatched half (waves 4-7) during the attention main loop, reset at its exit; on top of all42
# baseline (speedup 1.0000x reference)
; #define WAIT_BAR(N) asm volatile("s_waitcnt vmcnt(" #N ") lgkmcnt(0)\n\ts_barrier":::"memory")
;   #define DMA_K(t,slot) glds16(ksrc+(long)(t)*KVBLK*PD,(unsigned)__builtin_amdgcn_readfirstlane(kdst+(slot)))
;   #define DMA_V(t,slot) glds16(vsrc+(long)(t)*KVBLK*PD,(unsigned)__builtin_amdgcn_readfirstlane(vdst+(slot)))
;   #define CMASK(P0,P1,t) do{int jb_=(t)-(NT-4); if(jb_>=0)cmask(P0,P1,jb_,qrel,hi);}while(0)
;   #define START(P0,P1) do{ const float rm=rowmax(P0,P1); resc=false; \
;     { const float dl=rm; mhat=fadd_s(mhat,dl); \
;       _Pragma("unroll") for(int r=0;r<16;++r){P0[r]=fsub_s(P0[r],dl);P1[r]=fsub_s(P1[r],dl);} \
;       _Pragma("unroll") for(int r=0;r<16;++r)negm[r]=-mhat; asm volatile("":"+v"(negm)); } \
;     _Pragma("unroll") for(int r=0;r<16;++r)P0[r]=__builtin_amdgcn_exp2f(P0[r]); }while(0)
;   #define ROT() do{sl_prev=sl_cur;sl_cur=sl_next;sl_next=(sl_next==(NSLOT-1)*SLOTB)?0:sl_next+SLOTB;}while(0)
;   #define CMASK(P0,P1,t) do{}while(0)
;   #define CMASK(P0,P1,t) do{int jb_=(t)-(NT-4); if(jb_>=0)cmask(P0,P1,jb_,qrel,hi);}while(0)
; template<int THRL> __device__ __forceinline__ void attn_unit(int b,int h,int qb,const bf16*Q,const bf16*__restrict__ K,const bf16*__restrict__ V,bf16*O,char*shm,const int wid){
;     ...
;   const int qrel=wid*QBLK+r32;
;     ...
;   bool resc=false;
;     ...
;   f32x16 pA0,pA1,pB0,pB1;
;   int sl_prev=0,sl_cur=0,sl_next=SLOTB;
;     ...
;   DMA_K(2,2*SLOTB);
;   WAIT_BAR(3);
;   qkt(pA0,pA1,Kbase,qr,negm,r32,hi);asm volatile("s_nop 15\n\ts_nop 7":"+v"(pA0),"+v"(pA1));CMASK(pA0,pA1,0);
;   START(pA0,pA1);
;   _Pragma("unroll") for(int r=0;r<16;++r)pA1[r]=__builtin_amdgcn_exp2f(pA1[r]);
;   WAIT_BAR(0);
;   DMA_K(3,0);DMA_V(1,SLOTB);
;   ROT();
;   kload8(kf,kp0+sl_cur);
;   WAIT_BAR(2);
.LBB0_1545:
	v_lshlrev_b32_e32 v0, 1, v210
	v_and_b32_e32 v217, 32, v0
	v_lshlrev_b32_e32 v0, 4, v210
	v_and_b32_e32 v0, 0xc0, v0
	v_lshl_or_b32 v215, v213, 8, v0
	v_add_u32_e32 v0, 0, v217
	v_add3_u32 v221, v0, v214, v215
	v_max3_f32 v0, v18, v19, v2
	v_max3_f32 v36, v20, v21, v3
	s_sub_i32 s3, 0x1000, s36
	v_max3_f32 v0, v0, v4, v5
	v_max3_f32 v36, v36, v24, v25
	s_lshr_b32 s3, s3, 6
	v_max3_f32 v0, v0, v22, v23
	v_max3_f32 v36, v36, v8, v9
	s_cmp_lg_u32 0, -1
	v_max3_f32 v0, v0, v6, v7
	v_max3_f32 v36, v36, v28, v29
	v_lshl_add_u64 v[198:199], v[34:35], 0, s[22:23]
	v_max3_f32 v0, v0, v26, v27
	v_max3_f32 v36, v36, v12, v13
	s_mov_b32 s8, 1
	v_max3_f32 v0, v0, v10, v11
	v_max3_f32 v36, v36, v32, v33
	s_mov_b32 s38, 0
	v_max3_f32 v0, v0, v30, v31
	v_max3_f32 v36, v36, v16, v17
	v_lshlrev_b32_e32 v222, 4, v213
	v_max3_f32 v0, v0, v14, v15
	s_nop 0
	v_max_f32_e32 v0, v0, v36
	s_nop 0
	v_mov_b32_e32 v36, v0
	s_nop 1
	v_permlane32_swap_b32_e32 v0, v36
	v_max_f32_e32 v0, v0, v36
	s_nop 0
	v_add_f32_e32 v219, v1, v0
	v_sub_f32_e32 v2, v2, v0
	v_sub_f32_e32 v3, v3, v0
	v_sub_f32_e32 v18, v18, v0
	v_sub_f32_e32 v19, v19, v0
	v_sub_f32_e32 v20, v20, v0
	s_nop 0
	v_xor_b32_e32 v48, 0x80000000, v219
	v_mov_b32_e32 v49, v48
	v_mov_b32_e32 v50, v48
	v_mov_b32_e32 v51, v48
	v_mov_b32_e32 v52, v48
	v_mov_b32_e32 v53, v48
	v_mov_b32_e32 v54, v48
	v_mov_b32_e32 v55, v48
	v_mov_b32_e32 v56, v48
	v_mov_b32_e32 v57, v48
	v_mov_b32_e32 v58, v48
	v_mov_b32_e32 v59, v48
	v_mov_b32_e32 v60, v48
	v_mov_b32_e32 v61, v48
	v_mov_b32_e32 v62, v48
	v_mov_b32_e32 v63, v48
	s_waitcnt vmcnt(0) lgkmcnt(0)
	s_barrier
	v_exp_f32_e32 v64, v2
	v_exp_f32_e32 v65, v3
	v_lshl_add_u64 v[2:3], v[196:197], 0, s[20:21]
	s_mov_b32 s9, m0
	s_mov_b32 m0, s46
	s_nop 0
	global_load_lds_dwordx4 v[2:3], off
	s_mov_b32 m0, s9
	s_cselect_b32 s9, 0, 0
	s_add_i32 s9, s9, s45
	s_add_i32 s9, s9, 0x8000
	s_mov_b32 s13, m0
	s_mov_b32 m0, s9
	s_nop 0
	global_load_lds_dwordx4 v[198:199], off
	s_mov_b32 m0, s13
	ds_read_b128 v[188:191], v220 offset:8192
	ds_read_b128 v[184:187], v220 offset:8704
	ds_read_b128 v[180:183], v220 offset:10240
	ds_read_b128 v[176:179], v220 offset:10752
	ds_read_b128 v[172:175], v220 offset:12288
	ds_read_b128 v[168:171], v220 offset:12800
	ds_read_b128 v[164:167], v220 offset:14336
	ds_read_b128 v[160:163], v220 offset:14848
	v_sub_f32_e32 v4, v4, v0
	v_sub_f32_e32 v21, v21, v0
	v_sub_f32_e32 v5, v5, v0
	v_sub_f32_e32 v22, v22, v0
	v_sub_f32_e32 v6, v6, v0
	v_sub_f32_e32 v23, v23, v0
	v_sub_f32_e32 v7, v7, v0
	v_sub_f32_e32 v24, v24, v0
	v_sub_f32_e32 v8, v8, v0
	v_sub_f32_e32 v25, v25, v0
	v_sub_f32_e32 v9, v9, v0
	v_sub_f32_e32 v26, v26, v0
	v_sub_f32_e32 v10, v10, v0
	v_sub_f32_e32 v27, v27, v0
	v_sub_f32_e32 v11, v11, v0
	v_sub_f32_e32 v28, v28, v0
	v_sub_f32_e32 v12, v12, v0
	v_sub_f32_e32 v29, v29, v0
	v_sub_f32_e32 v13, v13, v0
	v_sub_f32_e32 v30, v30, v0
	v_sub_f32_e32 v14, v14, v0
	v_sub_f32_e32 v31, v31, v0
	v_sub_f32_e32 v15, v15, v0
	v_sub_f32_e32 v32, v32, v0
	v_sub_f32_e32 v16, v16, v0
	v_sub_f32_e32 v33, v33, v0
	v_sub_f32_e32 v0, v17, v0
	v_exp_f32_e32 v80, v18
	v_exp_f32_e32 v81, v19
	v_exp_f32_e32 v82, v20
	v_exp_f32_e32 v83, v21
	v_exp_f32_e32 v84, v22
	v_exp_f32_e32 v85, v23
	v_exp_f32_e32 v86, v24
	v_exp_f32_e32 v87, v25
	v_exp_f32_e32 v88, v26
	v_exp_f32_e32 v89, v27
	v_exp_f32_e32 v90, v28
	v_exp_f32_e32 v91, v29
	v_exp_f32_e32 v92, v30
	v_exp_f32_e32 v93, v31
	v_exp_f32_e32 v94, v32
	v_exp_f32_e32 v95, v33
	v_exp_f32_e32 v66, v4
	v_exp_f32_e32 v67, v5
	v_exp_f32_e32 v68, v6
	v_exp_f32_e32 v69, v7
	v_exp_f32_e32 v70, v8
	v_exp_f32_e32 v71, v9
	v_exp_f32_e32 v72, v10
	v_exp_f32_e32 v73, v11
	v_exp_f32_e32 v74, v12
	v_exp_f32_e32 v75, v13
	v_exp_f32_e32 v76, v14
	v_exp_f32_e32 v77, v15
	v_exp_f32_e32 v78, v16
	v_exp_f32_e32 v79, v0
	s_waitcnt vmcnt(2) lgkmcnt(0)
	s_barrier
	s_andn2_b64 vcc, exec, s[6:7]
	v_cmp_gt_u32_e64 s[6:7], 32, v210
	s_cbranch_vccnz .LBB0_1561
	s_cmpk_lt_u32 s79, 0x100
	s_cbranch_scc1 .Latp_skip
	s_setprio 1
.Latp_skip:
	v_mov_b32_e32 v14, v1
	v_mov_b32_e32 v15, v1
	v_lshl_add_u64 v[200:201], v[34:35], 0, s[20:21]
	v_mov_b32_e32 v0, v1
	v_mov_b32_e32 v2, v1
	v_mov_b32_e32 v3, v1
	v_mov_b32_e32 v4, v1
	v_mov_b32_e32 v5, v1
	v_mov_b32_e32 v6, v1
	v_mov_b32_e32 v7, v1
	v_mov_b32_e32 v8, v1
	v_mov_b32_e32 v9, v1
	v_mov_b32_e32 v10, v1
	v_mov_b32_e32 v11, v1
	v_mov_b32_e32 v12, v1
	v_mov_b32_e32 v13, v1
	v_mov_b64_e32 v[46:47], v[14:15]
	v_mov_b64_e32 v[30:31], v[14:15]
	v_lshl_add_u32 v204, v212, 2, s48
	v_lshl_add_u64 v[202:203], v[196:197], 0, s[24:25]
	s_mov_b32 s8, 0
	s_movk_i32 s38, 0x4000
	s_movk_i32 s40, 0x2000
	v_mov_b32_e32 v223, 0
	s_mov_b32 s39, 6
	v_mov_b64_e32 v[44:45], v[12:13]
	v_mov_b64_e32 v[42:43], v[10:11]
	v_mov_b64_e32 v[40:41], v[8:9]
	v_mov_b64_e32 v[38:39], v[6:7]
	v_mov_b64_e32 v[36:37], v[4:5]
	v_mov_b64_e32 v[34:35], v[2:3]
	v_mov_b64_e32 v[32:33], v[0:1]
	v_mov_b64_e32 v[28:29], v[12:13]
	v_mov_b64_e32 v[26:27], v[10:11]
	v_mov_b64_e32 v[24:25], v[8:9]
	v_mov_b64_e32 v[22:23], v[6:7]
	v_mov_b64_e32 v[20:21], v[4:5]
	v_mov_b64_e32 v[18:19], v[2:3]
	v_mov_b64_e32 v[16:17], v[0:1]

; #define WAIT_BAR(N) asm volatile("s_waitcnt vmcnt(" #N ") lgkmcnt(0)\n\ts_barrier":::"memory")
;   #define RESC() do{ if(resc){ asm volatile("s_waitcnt lgkmcnt(0)":::"memory"); \
;       _Pragma("unroll") for(int d_=0;d_<2;++d_) _Pragma("unroll") for(int r=0;r<16;++r)o[d_][r]*=wsf[crow(r,hi)]; } }while(0)
;   #define ROT() do{sl_prev=sl_cur;sl_cur=sl_next;sl_next=(sl_next==(NSLOT-1)*SLOTB)?0:sl_next+SLOTB;}while(0)
; template<int THRL> __device__ __forceinline__ void attn_unit(int b,int h,int qb,const bf16*Q,const bf16*__restrict__ K,const bf16*__restrict__ V,bf16*O,char*shm,const int wid){
;     ...
;   for(;t+5<NT;t+=2){
;     STEP(pB0,pB1,pA0,pA1,t,true,true,true);     WAIT_BAR(2); RESC(); ROT();
;     STEP(pA0,pA1,pB0,pB1,t+1,true,true,true);   WAIT_BAR(2); RESC(); ROT();
;   }
;     ...
;   for(;t+1<NT;t+=2){
.LBB0_1568:
	s_setprio 0
	s_add_i32 s8, s39, -3
	s_and_b32 s54, s37, 0x3c0
	s_add_i32 s6, s8, 1
	s_cmp_ge_u32 s6, s3
	s_cbranch_scc1 .LBB0_1562
